# nt policy on the P7 ACT output stores (largest write stream, not re-read until P9), on top of the nt streaming-load + hand LN_in version
# speedup vs baseline: 1.0232x; 1.0043x over previous
.LBB0_1104:
	v_mov_b32_e32 v228, 0xbfb8aa3b
	v_mov_b32_e32 v229, 0xbfb8aa3b
	v_mov_b32_e32 v230, 1.0
	v_mov_b32_e32 v231, 1.0
	v_readlane_b32 s90, v240, 36
	v_readlane_b32 s91, v240, 37
	v_readlane_b32 s35, v240, 38
	v_readlane_b32 s45, v240, 39
	v_cmp_eq_u32_e64 s[52:53], 0, v154
	s_add_u32 s74, s90, 0x0
	s_addc_u32 s75, s91, 0
	s_add_u32 s76, s90, 0x5800
	s_addc_u32 s77, s91, 0
	s_add_u32 s78, s90, 0xb000
	s_addc_u32 s79, s91, 0
	s_add_u32 s80, s90, 0x2c00
	s_addc_u32 s81, s91, 0
	s_add_u32 s82, s90, 0x8400
	s_addc_u32 s83, s91, 0
	s_add_u32 s84, s90, 0xdc00
	s_addc_u32 s85, s91, 0
	s_add_u32 s86, s35, 0
	s_addc_u32 s87, s45, 0
	s_add_u32 s88, s35, 0x2c00
	s_addc_u32 s89, s45, 0
	s_add_u32 s48, s94, 0x6500000
	s_addc_u32 s49, s95, 0
	s_add_u32 s50, s94, 0x1d600000
	s_addc_u32 s51, s95, 0
	v_lshl_or_b32 v128, s46, 7, v191
	s_lshl_b32 s47, s44, 8
	v_add_u32_e32 v129, s47, v155
	v_mul_u32_u24_e32 v129, 0x1600, v129
	v_lshl_add_u32 v129, v128, 1, v129
	v_lshlrev_b32_e32 v128, 2, v128
	global_load_dwordx4 v[196:199], v128, s[74:75]
	global_load_dwordx4 v[200:203], v128, s[76:77]
	global_load_dwordx4 v[204:207], v128, s[78:79]
	global_load_dwordx4 v[208:211], v128, s[86:87]
	global_load_dwordx4 v[212:215], v128, s[80:81]
	global_load_dwordx4 v[216:219], v128, s[82:83]
	global_load_dwordx4 v[220:223], v128, s[84:85]
	global_load_dwordx4 v[224:227], v128, s[88:89]
	s_lshl_b32 s47, s44, 4
	s_lshl_b32 s90, s33, 2
	s_add_i32 s47, s47, s90
	v_lshl_or_b32 v132, s46, 8, v191
	v_add_u32_e32 v130, s47, v154
	v_add_u32_e32 v131, s47, v156
	v_mul_u32_u24_e32 v130, 0x2c00, v130
	v_mul_u32_u24_e32 v131, 0x2c00, v131
	v_lshl_add_u32 v130, v132, 1, v130
	v_lshl_add_u32 v131, v132, 1, v131
	s_mov_b64 exec, s[0:1]
	v_cvt_pk_bf16_f32 v120, v142, v143
	v_cvt_pk_bf16_f32 v121, v144, v145
	v_cvt_pk_bf16_f32 v122, v60, v61
	v_cvt_pk_bf16_f32 v123, v62, v63
	global_store_dwordx4 v130, v[120:123], s[50:51]
	v_cvt_pk_bf16_f32 v124, v108, v109
	v_cvt_pk_bf16_f32 v125, v110, v111
	v_cvt_pk_bf16_f32 v126, v56, v57
	v_cvt_pk_bf16_f32 v127, v58, v59
	global_store_dwordx4 v130, v[124:127], s[50:51] offset:256
	s_mov_b64 exec, s[6:7]
	v_cvt_pk_bf16_f32 v120, v100, v101
	v_cvt_pk_bf16_f32 v121, v102, v103
	v_cvt_pk_bf16_f32 v122, v36, v37
	v_cvt_pk_bf16_f32 v123, v38, v39
	global_store_dwordx4 v131, v[120:123], s[50:51]
	v_cvt_pk_bf16_f32 v124, v96, v97
	v_cvt_pk_bf16_f32 v125, v98, v99
	v_cvt_pk_bf16_f32 v126, v32, v33
	v_cvt_pk_bf16_f32 v127, v34, v35
	global_store_dwordx4 v131, v[124:127], s[50:51] offset:256
	s_mov_b64 exec, s[0:1]
	v_cvt_pk_bf16_f32 v120, v92, v93
	v_cvt_pk_bf16_f32 v121, v94, v95
	v_cvt_pk_bf16_f32 v122, v28, v29
	v_cvt_pk_bf16_f32 v123, v30, v31
	v_add_u32_e32 v132, 0x16000, v130
	global_store_dwordx4 v132, v[120:123], s[50:51]
	v_cvt_pk_bf16_f32 v124, v88, v89
	v_cvt_pk_bf16_f32 v125, v90, v91
	v_cvt_pk_bf16_f32 v126, v24, v25
	v_cvt_pk_bf16_f32 v127, v26, v27
	v_add_u32_e32 v132, 0x16100, v130
	global_store_dwordx4 v132, v[124:127], s[50:51]
	s_mov_b64 exec, s[6:7]
	v_cvt_pk_bf16_f32 v120, v68, v69
	v_cvt_pk_bf16_f32 v121, v70, v71
	v_cvt_pk_bf16_f32 v122, v4, v5
	v_cvt_pk_bf16_f32 v123, v6, v7
	v_add_u32_e32 v132, 0x16000, v131
	global_store_dwordx4 v132, v[120:123], s[50:51]
	v_cvt_pk_bf16_f32 v124, v64, v65
	v_cvt_pk_bf16_f32 v125, v66, v67
	v_cvt_pk_bf16_f32 v126, v0, v1
	v_cvt_pk_bf16_f32 v127, v2, v3
	v_add_u32_e32 v132, 0x16100, v131
	global_store_dwordx4 v132, v[124:127], s[50:51]
	s_mov_b64 exec, -1
	s_waitcnt vmcnt(8)
	v_cndmask_b32_e64 v166, 0, v200, s[52:53]
	v_cndmask_b32_e64 v170, 0, v196, s[0:1]
	v_cndmask_b32_e64 v174, 0, v216, s[52:53]
	v_cndmask_b32_e64 v178, 0, v212, s[0:1]
	v_cndmask_b32_e64 v167, 0, v201, s[52:53]
	v_cndmask_b32_e64 v171, 0, v197, s[0:1]
	v_cndmask_b32_e64 v175, 0, v217, s[52:53]
	v_cndmask_b32_e64 v179, 0, v213, s[0:1]
	v_cndmask_b32_e64 v168, 0, v202, s[52:53]
	v_cndmask_b32_e64 v172, 0, v198, s[0:1]
	v_cndmask_b32_e64 v176, 0, v218, s[52:53]
	v_cndmask_b32_e64 v180, 0, v214, s[0:1]
	v_cndmask_b32_e64 v169, 0, v203, s[52:53]
	v_cndmask_b32_e64 v173, 0, v199, s[0:1]
	v_cndmask_b32_e64 v177, 0, v219, s[52:53]
	v_cndmask_b32_e64 v181, 0, v215, s[0:1]
	v_pk_fma_f32 v[182:183], v[204:205], v[100:101], v[208:209]
	v_pk_fma_f32 v[184:185], v[206:207], v[102:103], v[210:211]
	v_pk_fma_f32 v[186:187], v[220:221], v[96:97], v[224:225]
	v_pk_fma_f32 v[188:189], v[222:223], v[98:99], v[226:227]
	v_fmac_f32_dpp v182, v100, v200 row_shr:1 row_mask:0xf bank_mask:0xf
	v_fmac_f32_dpp v183, v101, v201 row_shr:1 row_mask:0xf bank_mask:0xf
	v_fmac_f32_dpp v184, v102, v202 row_shr:1 row_mask:0xf bank_mask:0xf
	v_fmac_f32_dpp v185, v103, v203 row_shr:1 row_mask:0xf bank_mask:0xf
	v_fmac_f32_dpp v186, v96, v216 row_shr:1 row_mask:0xf bank_mask:0xf
	v_fmac_f32_dpp v187, v97, v217 row_shr:1 row_mask:0xf bank_mask:0xf
	v_fmac_f32_dpp v188, v98, v218 row_shr:1 row_mask:0xf bank_mask:0xf
	v_fmac_f32_dpp v189, v99, v219 row_shr:1 row_mask:0xf bank_mask:0xf
	v_fmac_f32_dpp v182, v100, v196 row_shr:2 row_mask:0xf bank_mask:0xf
	v_fmac_f32_dpp v183, v101, v197 row_shr:2 row_mask:0xf bank_mask:0xf
	v_fmac_f32_dpp v184, v102, v198 row_shr:2 row_mask:0xf bank_mask:0xf
	v_fmac_f32_dpp v185, v103, v199 row_shr:2 row_mask:0xf bank_mask:0xf
	v_fmac_f32_dpp v186, v96, v212 row_shr:2 row_mask:0xf bank_mask:0xf
	v_fmac_f32_dpp v187, v97, v213 row_shr:2 row_mask:0xf bank_mask:0xf
	v_fmac_f32_dpp v188, v98, v214 row_shr:2 row_mask:0xf bank_mask:0xf
	v_fmac_f32_dpp v189, v99, v215 row_shr:2 row_mask:0xf bank_mask:0xf
	v_fmac_f32_dpp v182, v112, v166 row_ror:1 row_mask:0xf bank_mask:0xf
	v_fmac_f32_dpp v183, v113, v167 row_ror:1 row_mask:0xf bank_mask:0xf
	v_fmac_f32_dpp v184, v114, v168 row_ror:1 row_mask:0xf bank_mask:0xf
	v_fmac_f32_dpp v185, v115, v169 row_ror:1 row_mask:0xf bank_mask:0xf
	v_fmac_f32_dpp v186, v104, v174 row_ror:1 row_mask:0xf bank_mask:0xf
	v_fmac_f32_dpp v187, v105, v175 row_ror:1 row_mask:0xf bank_mask:0xf
	v_fmac_f32_dpp v188, v106, v176 row_ror:1 row_mask:0xf bank_mask:0xf
	v_fmac_f32_dpp v189, v107, v177 row_ror:1 row_mask:0xf bank_mask:0xf
	v_fmac_f32_dpp v182, v112, v170 row_ror:2 row_mask:0xf bank_mask:0xf
	v_fmac_f32_dpp v183, v113, v171 row_ror:2 row_mask:0xf bank_mask:0xf
	v_fmac_f32_dpp v184, v114, v172 row_ror:2 row_mask:0xf bank_mask:0xf
	v_fmac_f32_dpp v185, v115, v173 row_ror:2 row_mask:0xf bank_mask:0xf
	v_fmac_f32_dpp v186, v104, v178 row_ror:2 row_mask:0xf bank_mask:0xf
	v_fmac_f32_dpp v187, v105, v179 row_ror:2 row_mask:0xf bank_mask:0xf
	v_fmac_f32_dpp v188, v106, v180 row_ror:2 row_mask:0xf bank_mask:0xf
	v_fmac_f32_dpp v189, v107, v181 row_ror:2 row_mask:0xf bank_mask:0xf
	v_pk_mul_f32 v[116:117], v[182:183], v[228:229]
	v_pk_mul_f32 v[118:119], v[184:185], v[228:229]
	v_exp_f32_e32 v116, v116
	v_exp_f32_e32 v117, v117
	v_exp_f32_e32 v118, v118
	v_exp_f32_e32 v119, v119
	v_pk_add_f32 v[116:117], v[116:117], v[230:231]
	v_pk_add_f32 v[118:119], v[118:119], v[230:231]
	v_rcp_f32_e32 v116, v116
	v_rcp_f32_e32 v117, v117
	v_rcp_f32_e32 v118, v118
	v_rcp_f32_e32 v119, v119
	v_pk_mul_f32 v[116:117], v[182:183], v[116:117]
	v_pk_mul_f32 v[118:119], v[184:185], v[118:119]
	v_pk_mul_f32 v[116:117], v[116:117], v[186:187]
	v_pk_mul_f32 v[118:119], v[118:119], v[188:189]
	v_cvt_pk_bf16_f32 v100, v116, v117
	v_cvt_pk_bf16_f32 v101, v118, v119
	v_pk_fma_f32 v[182:183], v[204:205], v[112:113], v[208:209]
	v_pk_fma_f32 v[184:185], v[206:207], v[114:115], v[210:211]
	v_pk_fma_f32 v[186:187], v[220:221], v[104:105], v[224:225]
	v_pk_fma_f32 v[188:189], v[222:223], v[106:107], v[226:227]
	v_fmac_f32_dpp v182, v112, v200 row_shr:1 row_mask:0xf bank_mask:0xf
	v_fmac_f32_dpp v183, v113, v201 row_shr:1 row_mask:0xf bank_mask:0xf
	v_fmac_f32_dpp v184, v114, v202 row_shr:1 row_mask:0xf bank_mask:0xf
	v_fmac_f32_dpp v185, v115, v203 row_shr:1 row_mask:0xf bank_mask:0xf
	v_fmac_f32_dpp v186, v104, v216 row_shr:1 row_mask:0xf bank_mask:0xf
	v_fmac_f32_dpp v187, v105, v217 row_shr:1 row_mask:0xf bank_mask:0xf
	v_fmac_f32_dpp v188, v106, v218 row_shr:1 row_mask:0xf bank_mask:0xf
	v_fmac_f32_dpp v189, v107, v219 row_shr:1 row_mask:0xf bank_mask:0xf
	v_fmac_f32_dpp v182, v112, v196 row_shr:2 row_mask:0xf bank_mask:0xf
	v_fmac_f32_dpp v183, v113, v197 row_shr:2 row_mask:0xf bank_mask:0xf
	v_fmac_f32_dpp v184, v114, v198 row_shr:2 row_mask:0xf bank_mask:0xf
	v_fmac_f32_dpp v185, v115, v199 row_shr:2 row_mask:0xf bank_mask:0xf
	v_fmac_f32_dpp v186, v104, v212 row_shr:2 row_mask:0xf bank_mask:0xf
	v_fmac_f32_dpp v187, v105, v213 row_shr:2 row_mask:0xf bank_mask:0xf
	v_fmac_f32_dpp v188, v106, v214 row_shr:2 row_mask:0xf bank_mask:0xf
	v_fmac_f32_dpp v189, v107, v215 row_shr:2 row_mask:0xf bank_mask:0xf
	v_fmac_f32_dpp v182, v138, v166 row_ror:1 row_mask:0xf bank_mask:0xf
	v_fmac_f32_dpp v183, v139, v167 row_ror:1 row_mask:0xf bank_mask:0xf
	v_fmac_f32_dpp v184, v140, v168 row_ror:1 row_mask:0xf bank_mask:0xf
	v_fmac_f32_dpp v185, v141, v169 row_ror:1 row_mask:0xf bank_mask:0xf
	v_fmac_f32_dpp v186, v134, v174 row_ror:1 row_mask:0xf bank_mask:0xf
	v_fmac_f32_dpp v187, v135, v175 row_ror:1 row_mask:0xf bank_mask:0xf
	v_fmac_f32_dpp v188, v136, v176 row_ror:1 row_mask:0xf bank_mask:0xf
	v_fmac_f32_dpp v189, v137, v177 row_ror:1 row_mask:0xf bank_mask:0xf
	v_fmac_f32_dpp v182, v138, v170 row_ror:2 row_mask:0xf bank_mask:0xf
	v_fmac_f32_dpp v183, v139, v171 row_ror:2 row_mask:0xf bank_mask:0xf
	v_fmac_f32_dpp v184, v140, v172 row_ror:2 row_mask:0xf bank_mask:0xf
	v_fmac_f32_dpp v185, v141, v173 row_ror:2 row_mask:0xf bank_mask:0xf
	v_fmac_f32_dpp v186, v134, v178 row_ror:2 row_mask:0xf bank_mask:0xf
	v_fmac_f32_dpp v187, v135, v179 row_ror:2 row_mask:0xf bank_mask:0xf
	v_fmac_f32_dpp v188, v136, v180 row_ror:2 row_mask:0xf bank_mask:0xf
	v_fmac_f32_dpp v189, v137, v181 row_ror:2 row_mask:0xf bank_mask:0xf
	v_pk_mul_f32 v[116:117], v[182:183], v[228:229]
	v_pk_mul_f32 v[118:119], v[184:185], v[228:229]
	v_exp_f32_e32 v116, v116
	v_exp_f32_e32 v117, v117
	v_exp_f32_e32 v118, v118
	v_exp_f32_e32 v119, v119
	v_pk_add_f32 v[116:117], v[116:117], v[230:231]
	v_pk_add_f32 v[118:119], v[118:119], v[230:231]
	v_rcp_f32_e32 v116, v116
	v_rcp_f32_e32 v117, v117
	v_rcp_f32_e32 v118, v118
	v_rcp_f32_e32 v119, v119
	v_pk_mul_f32 v[116:117], v[182:183], v[116:117]
	v_pk_mul_f32 v[118:119], v[184:185], v[118:119]
	v_pk_mul_f32 v[116:117], v[116:117], v[186:187]
	v_pk_mul_f32 v[118:119], v[118:119], v[188:189]
	v_cvt_pk_bf16_f32 v112, v116, v117
	v_cvt_pk_bf16_f32 v113, v118, v119
	v_pk_fma_f32 v[182:183], v[204:205], v[138:139], v[208:209]
	v_pk_fma_f32 v[184:185], v[206:207], v[140:141], v[210:211]
	v_pk_fma_f32 v[186:187], v[220:221], v[134:135], v[224:225]
	v_pk_fma_f32 v[188:189], v[222:223], v[136:137], v[226:227]
	v_fmac_f32_dpp v182, v138, v200 row_shr:1 row_mask:0xf bank_mask:0xf
	v_fmac_f32_dpp v183, v139, v201 row_shr:1 row_mask:0xf bank_mask:0xf
	v_fmac_f32_dpp v184, v140, v202 row_shr:1 row_mask:0xf bank_mask:0xf
	v_fmac_f32_dpp v185, v141, v203 row_shr:1 row_mask:0xf bank_mask:0xf
	v_fmac_f32_dpp v186, v134, v216 row_shr:1 row_mask:0xf bank_mask:0xf
	v_fmac_f32_dpp v187, v135, v217 row_shr:1 row_mask:0xf bank_mask:0xf
	v_fmac_f32_dpp v188, v136, v218 row_shr:1 row_mask:0xf bank_mask:0xf
	v_fmac_f32_dpp v189, v137, v219 row_shr:1 row_mask:0xf bank_mask:0xf
	v_fmac_f32_dpp v182, v138, v196 row_shr:2 row_mask:0xf bank_mask:0xf
	v_fmac_f32_dpp v183, v139, v197 row_shr:2 row_mask:0xf bank_mask:0xf
	v_fmac_f32_dpp v184, v140, v198 row_shr:2 row_mask:0xf bank_mask:0xf
	v_fmac_f32_dpp v185, v141, v199 row_shr:2 row_mask:0xf bank_mask:0xf
	v_fmac_f32_dpp v186, v134, v212 row_shr:2 row_mask:0xf bank_mask:0xf
	v_fmac_f32_dpp v187, v135, v213 row_shr:2 row_mask:0xf bank_mask:0xf
	v_fmac_f32_dpp v188, v136, v214 row_shr:2 row_mask:0xf bank_mask:0xf
	v_fmac_f32_dpp v189, v137, v215 row_shr:2 row_mask:0xf bank_mask:0xf
	v_fmac_f32_dpp v182, v142, v166 row_ror:1 row_mask:0xf bank_mask:0xf
	v_fmac_f32_dpp v183, v143, v167 row_ror:1 row_mask:0xf bank_mask:0xf
	v_fmac_f32_dpp v184, v144, v168 row_ror:1 row_mask:0xf bank_mask:0xf
	v_fmac_f32_dpp v185, v145, v169 row_ror:1 row_mask:0xf bank_mask:0xf
	v_fmac_f32_dpp v186, v108, v174 row_ror:1 row_mask:0xf bank_mask:0xf
	v_fmac_f32_dpp v187, v109, v175 row_ror:1 row_mask:0xf bank_mask:0xf
	v_fmac_f32_dpp v188, v110, v176 row_ror:1 row_mask:0xf bank_mask:0xf
	v_fmac_f32_dpp v189, v111, v177 row_ror:1 row_mask:0xf bank_mask:0xf
	v_fmac_f32_dpp v182, v142, v170 row_ror:2 row_mask:0xf bank_mask:0xf
	v_fmac_f32_dpp v183, v143, v171 row_ror:2 row_mask:0xf bank_mask:0xf
	v_fmac_f32_dpp v184, v144, v172 row_ror:2 row_mask:0xf bank_mask:0xf
	v_fmac_f32_dpp v185, v145, v173 row_ror:2 row_mask:0xf bank_mask:0xf
	v_fmac_f32_dpp v186, v108, v178 row_ror:2 row_mask:0xf bank_mask:0xf
	v_fmac_f32_dpp v187, v109, v179 row_ror:2 row_mask:0xf bank_mask:0xf
	v_fmac_f32_dpp v188, v110, v180 row_ror:2 row_mask:0xf bank_mask:0xf
	v_fmac_f32_dpp v189, v111, v181 row_ror:2 row_mask:0xf bank_mask:0xf
	v_pk_mul_f32 v[116:117], v[182:183], v[228:229]
	v_pk_mul_f32 v[118:119], v[184:185], v[228:229]
	v_exp_f32_e32 v116, v116
	v_exp_f32_e32 v117, v117
	v_exp_f32_e32 v118, v118
	v_exp_f32_e32 v119, v119
	v_pk_add_f32 v[116:117], v[116:117], v[230:231]
	v_pk_add_f32 v[118:119], v[118:119], v[230:231]
	v_rcp_f32_e32 v116, v116
	v_rcp_f32_e32 v117, v117
	v_rcp_f32_e32 v118, v118
	v_rcp_f32_e32 v119, v119
	v_pk_mul_f32 v[116:117], v[182:183], v[116:117]
	v_pk_mul_f32 v[118:119], v[184:185], v[118:119]
	v_pk_mul_f32 v[116:117], v[116:117], v[186:187]
	v_pk_mul_f32 v[118:119], v[118:119], v[188:189]
	v_cvt_pk_bf16_f32 v138, v116, v117
	v_cvt_pk_bf16_f32 v139, v118, v119
	v_pk_fma_f32 v[182:183], v[204:205], v[142:143], v[208:209]
	v_pk_fma_f32 v[184:185], v[206:207], v[144:145], v[210:211]
	v_pk_fma_f32 v[186:187], v[220:221], v[108:109], v[224:225]
	v_pk_fma_f32 v[188:189], v[222:223], v[110:111], v[226:227]
	v_fmac_f32_dpp v182, v142, v200 row_shr:1 row_mask:0xf bank_mask:0xf
	v_fmac_f32_dpp v183, v143, v201 row_shr:1 row_mask:0xf bank_mask:0xf
	v_fmac_f32_dpp v184, v144, v202 row_shr:1 row_mask:0xf bank_mask:0xf
	v_fmac_f32_dpp v185, v145, v203 row_shr:1 row_mask:0xf bank_mask:0xf
	v_fmac_f32_dpp v186, v108, v216 row_shr:1 row_mask:0xf bank_mask:0xf
	v_fmac_f32_dpp v187, v109, v217 row_shr:1 row_mask:0xf bank_mask:0xf
	v_fmac_f32_dpp v188, v110, v218 row_shr:1 row_mask:0xf bank_mask:0xf
	v_fmac_f32_dpp v189, v111, v219 row_shr:1 row_mask:0xf bank_mask:0xf
	v_fmac_f32_dpp v182, v142, v196 row_shr:2 row_mask:0xf bank_mask:0xf
	v_fmac_f32_dpp v183, v143, v197 row_shr:2 row_mask:0xf bank_mask:0xf
	v_fmac_f32_dpp v184, v144, v198 row_shr:2 row_mask:0xf bank_mask:0xf
	v_fmac_f32_dpp v185, v145, v199 row_shr:2 row_mask:0xf bank_mask:0xf
	v_fmac_f32_dpp v186, v108, v212 row_shr:2 row_mask:0xf bank_mask:0xf
	v_fmac_f32_dpp v187, v109, v213 row_shr:2 row_mask:0xf bank_mask:0xf
	v_fmac_f32_dpp v188, v110, v214 row_shr:2 row_mask:0xf bank_mask:0xf
	v_fmac_f32_dpp v189, v111, v215 row_shr:2 row_mask:0xf bank_mask:0xf
	v_pk_mul_f32 v[116:117], v[182:183], v[228:229]
	v_pk_mul_f32 v[118:119], v[184:185], v[228:229]
	v_exp_f32_e32 v116, v116
	v_exp_f32_e32 v117, v117
	v_exp_f32_e32 v118, v118
	v_exp_f32_e32 v119, v119
	v_pk_add_f32 v[116:117], v[116:117], v[230:231]
	v_pk_add_f32 v[118:119], v[118:119], v[230:231]
	v_rcp_f32_e32 v116, v116
	v_rcp_f32_e32 v117, v117
	v_rcp_f32_e32 v118, v118
	v_rcp_f32_e32 v119, v119
	v_pk_mul_f32 v[116:117], v[182:183], v[116:117]
	v_pk_mul_f32 v[118:119], v[184:185], v[118:119]
	v_pk_mul_f32 v[116:117], v[116:117], v[186:187]
	v_pk_mul_f32 v[118:119], v[118:119], v[188:189]
	v_cvt_pk_bf16_f32 v142, v116, v117
	v_cvt_pk_bf16_f32 v143, v118, v119
	v_pk_fma_f32 v[182:183], v[204:205], v[68:69], v[208:209]
	v_pk_fma_f32 v[184:185], v[206:207], v[70:71], v[210:211]
	v_pk_fma_f32 v[186:187], v[220:221], v[64:65], v[224:225]
	v_pk_fma_f32 v[188:189], v[222:223], v[66:67], v[226:227]
	v_fmac_f32_dpp v182, v68, v200 row_shr:1 row_mask:0xf bank_mask:0xf
	v_fmac_f32_dpp v183, v69, v201 row_shr:1 row_mask:0xf bank_mask:0xf
	v_fmac_f32_dpp v184, v70, v202 row_shr:1 row_mask:0xf bank_mask:0xf
	v_fmac_f32_dpp v185, v71, v203 row_shr:1 row_mask:0xf bank_mask:0xf
	v_fmac_f32_dpp v186, v64, v216 row_shr:1 row_mask:0xf bank_mask:0xf
	v_fmac_f32_dpp v187, v65, v217 row_shr:1 row_mask:0xf bank_mask:0xf
	v_fmac_f32_dpp v188, v66, v218 row_shr:1 row_mask:0xf bank_mask:0xf
	v_fmac_f32_dpp v189, v67, v219 row_shr:1 row_mask:0xf bank_mask:0xf
	v_fmac_f32_dpp v182, v68, v196 row_shr:2 row_mask:0xf bank_mask:0xf
	v_fmac_f32_dpp v183, v69, v197 row_shr:2 row_mask:0xf bank_mask:0xf
	v_fmac_f32_dpp v184, v70, v198 row_shr:2 row_mask:0xf bank_mask:0xf
	v_fmac_f32_dpp v185, v71, v199 row_shr:2 row_mask:0xf bank_mask:0xf
	v_fmac_f32_dpp v186, v64, v212 row_shr:2 row_mask:0xf bank_mask:0xf
	v_fmac_f32_dpp v187, v65, v213 row_shr:2 row_mask:0xf bank_mask:0xf
	v_fmac_f32_dpp v188, v66, v214 row_shr:2 row_mask:0xf bank_mask:0xf
	v_fmac_f32_dpp v189, v67, v215 row_shr:2 row_mask:0xf bank_mask:0xf
	v_fmac_f32_dpp v182, v76, v166 row_ror:1 row_mask:0xf bank_mask:0xf
	v_fmac_f32_dpp v183, v77, v167 row_ror:1 row_mask:0xf bank_mask:0xf
	v_fmac_f32_dpp v184, v78, v168 row_ror:1 row_mask:0xf bank_mask:0xf
	v_fmac_f32_dpp v185, v79, v169 row_ror:1 row_mask:0xf bank_mask:0xf
	v_fmac_f32_dpp v186, v72, v174 row_ror:1 row_mask:0xf bank_mask:0xf
	v_fmac_f32_dpp v187, v73, v175 row_ror:1 row_mask:0xf bank_mask:0xf
	v_fmac_f32_dpp v188, v74, v176 row_ror:1 row_mask:0xf bank_mask:0xf
	v_fmac_f32_dpp v189, v75, v177 row_ror:1 row_mask:0xf bank_mask:0xf
	v_fmac_f32_dpp v182, v76, v170 row_ror:2 row_mask:0xf bank_mask:0xf
	v_fmac_f32_dpp v183, v77, v171 row_ror:2 row_mask:0xf bank_mask:0xf
	v_fmac_f32_dpp v184, v78, v172 row_ror:2 row_mask:0xf bank_mask:0xf
	v_fmac_f32_dpp v185, v79, v173 row_ror:2 row_mask:0xf bank_mask:0xf
	v_fmac_f32_dpp v186, v72, v178 row_ror:2 row_mask:0xf bank_mask:0xf
	v_fmac_f32_dpp v187, v73, v179 row_ror:2 row_mask:0xf bank_mask:0xf
	v_fmac_f32_dpp v188, v74, v180 row_ror:2 row_mask:0xf bank_mask:0xf
	v_fmac_f32_dpp v189, v75, v181 row_ror:2 row_mask:0xf bank_mask:0xf
	v_pk_mul_f32 v[116:117], v[182:183], v[228:229]
	v_pk_mul_f32 v[118:119], v[184:185], v[228:229]
	v_exp_f32_e32 v116, v116
	v_exp_f32_e32 v117, v117
	v_exp_f32_e32 v118, v118
	v_exp_f32_e32 v119, v119
	v_pk_add_f32 v[116:117], v[116:117], v[230:231]
	v_pk_add_f32 v[118:119], v[118:119], v[230:231]
	v_rcp_f32_e32 v116, v116
	v_rcp_f32_e32 v117, v117
	v_rcp_f32_e32 v118, v118
	v_rcp_f32_e32 v119, v119
	v_pk_mul_f32 v[116:117], v[182:183], v[116:117]
	v_pk_mul_f32 v[118:119], v[184:185], v[118:119]
	v_pk_mul_f32 v[116:117], v[116:117], v[186:187]
	v_pk_mul_f32 v[118:119], v[118:119], v[188:189]
	v_cvt_pk_bf16_f32 v68, v116, v117
	v_cvt_pk_bf16_f32 v69, v118, v119
	v_pk_fma_f32 v[182:183], v[204:205], v[76:77], v[208:209]
	v_pk_fma_f32 v[184:185], v[206:207], v[78:79], v[210:211]
	v_pk_fma_f32 v[186:187], v[220:221], v[72:73], v[224:225]
	v_pk_fma_f32 v[188:189], v[222:223], v[74:75], v[226:227]
	v_fmac_f32_dpp v182, v76, v200 row_shr:1 row_mask:0xf bank_mask:0xf
	v_fmac_f32_dpp v183, v77, v201 row_shr:1 row_mask:0xf bank_mask:0xf
	v_fmac_f32_dpp v184, v78, v202 row_shr:1 row_mask:0xf bank_mask:0xf
	v_fmac_f32_dpp v185, v79, v203 row_shr:1 row_mask:0xf bank_mask:0xf
	v_fmac_f32_dpp v186, v72, v216 row_shr:1 row_mask:0xf bank_mask:0xf
	v_fmac_f32_dpp v187, v73, v217 row_shr:1 row_mask:0xf bank_mask:0xf
	v_fmac_f32_dpp v188, v74, v218 row_shr:1 row_mask:0xf bank_mask:0xf
	v_fmac_f32_dpp v189, v75, v219 row_shr:1 row_mask:0xf bank_mask:0xf
	v_fmac_f32_dpp v182, v76, v196 row_shr:2 row_mask:0xf bank_mask:0xf
	v_fmac_f32_dpp v183, v77, v197 row_shr:2 row_mask:0xf bank_mask:0xf
	v_fmac_f32_dpp v184, v78, v198 row_shr:2 row_mask:0xf bank_mask:0xf
	v_fmac_f32_dpp v185, v79, v199 row_shr:2 row_mask:0xf bank_mask:0xf
	v_fmac_f32_dpp v186, v72, v212 row_shr:2 row_mask:0xf bank_mask:0xf
	v_fmac_f32_dpp v187, v73, v213 row_shr:2 row_mask:0xf bank_mask:0xf
	v_fmac_f32_dpp v188, v74, v214 row_shr:2 row_mask:0xf bank_mask:0xf
	v_fmac_f32_dpp v189, v75, v215 row_shr:2 row_mask:0xf bank_mask:0xf
	v_fmac_f32_dpp v182, v84, v166 row_ror:1 row_mask:0xf bank_mask:0xf
	v_fmac_f32_dpp v183, v85, v167 row_ror:1 row_mask:0xf bank_mask:0xf
	v_fmac_f32_dpp v184, v86, v168 row_ror:1 row_mask:0xf bank_mask:0xf
	v_fmac_f32_dpp v185, v87, v169 row_ror:1 row_mask:0xf bank_mask:0xf
	v_fmac_f32_dpp v186, v80, v174 row_ror:1 row_mask:0xf bank_mask:0xf
	v_fmac_f32_dpp v187, v81, v175 row_ror:1 row_mask:0xf bank_mask:0xf
	v_fmac_f32_dpp v188, v82, v176 row_ror:1 row_mask:0xf bank_mask:0xf
	v_fmac_f32_dpp v189, v83, v177 row_ror:1 row_mask:0xf bank_mask:0xf
	v_fmac_f32_dpp v182, v84, v170 row_ror:2 row_mask:0xf bank_mask:0xf
	v_fmac_f32_dpp v183, v85, v171 row_ror:2 row_mask:0xf bank_mask:0xf
	v_fmac_f32_dpp v184, v86, v172 row_ror:2 row_mask:0xf bank_mask:0xf
	v_fmac_f32_dpp v185, v87, v173 row_ror:2 row_mask:0xf bank_mask:0xf
	v_fmac_f32_dpp v186, v80, v178 row_ror:2 row_mask:0xf bank_mask:0xf
	v_fmac_f32_dpp v187, v81, v179 row_ror:2 row_mask:0xf bank_mask:0xf
	v_fmac_f32_dpp v188, v82, v180 row_ror:2 row_mask:0xf bank_mask:0xf
	v_fmac_f32_dpp v189, v83, v181 row_ror:2 row_mask:0xf bank_mask:0xf
	v_pk_mul_f32 v[116:117], v[182:183], v[228:229]
	v_pk_mul_f32 v[118:119], v[184:185], v[228:229]
	v_exp_f32_e32 v116, v116
	v_exp_f32_e32 v117, v117
	v_exp_f32_e32 v118, v118
	v_exp_f32_e32 v119, v119
	v_pk_add_f32 v[116:117], v[116:117], v[230:231]
	v_pk_add_f32 v[118:119], v[118:119], v[230:231]
	v_rcp_f32_e32 v116, v116
	v_rcp_f32_e32 v117, v117
	v_rcp_f32_e32 v118, v118
	v_rcp_f32_e32 v119, v119
	v_pk_mul_f32 v[116:117], v[182:183], v[116:117]
	v_pk_mul_f32 v[118:119], v[184:185], v[118:119]
	v_pk_mul_f32 v[116:117], v[116:117], v[186:187]
	v_pk_mul_f32 v[118:119], v[118:119], v[188:189]
	v_cvt_pk_bf16_f32 v76, v116, v117
	v_cvt_pk_bf16_f32 v77, v118, v119
	v_pk_fma_f32 v[182:183], v[204:205], v[84:85], v[208:209]
	v_pk_fma_f32 v[184:185], v[206:207], v[86:87], v[210:211]
	v_pk_fma_f32 v[186:187], v[220:221], v[80:81], v[224:225]
	v_pk_fma_f32 v[188:189], v[222:223], v[82:83], v[226:227]
	v_fmac_f32_dpp v182, v84, v200 row_shr:1 row_mask:0xf bank_mask:0xf
	v_fmac_f32_dpp v183, v85, v201 row_shr:1 row_mask:0xf bank_mask:0xf
	v_fmac_f32_dpp v184, v86, v202 row_shr:1 row_mask:0xf bank_mask:0xf
	v_fmac_f32_dpp v185, v87, v203 row_shr:1 row_mask:0xf bank_mask:0xf
	v_fmac_f32_dpp v186, v80, v216 row_shr:1 row_mask:0xf bank_mask:0xf
	v_fmac_f32_dpp v187, v81, v217 row_shr:1 row_mask:0xf bank_mask:0xf
	v_fmac_f32_dpp v188, v82, v218 row_shr:1 row_mask:0xf bank_mask:0xf
	v_fmac_f32_dpp v189, v83, v219 row_shr:1 row_mask:0xf bank_mask:0xf
	v_fmac_f32_dpp v182, v84, v196 row_shr:2 row_mask:0xf bank_mask:0xf
	v_fmac_f32_dpp v183, v85, v197 row_shr:2 row_mask:0xf bank_mask:0xf
	v_fmac_f32_dpp v184, v86, v198 row_shr:2 row_mask:0xf bank_mask:0xf
	v_fmac_f32_dpp v185, v87, v199 row_shr:2 row_mask:0xf bank_mask:0xf
	v_fmac_f32_dpp v186, v80, v212 row_shr:2 row_mask:0xf bank_mask:0xf
	v_fmac_f32_dpp v187, v81, v213 row_shr:2 row_mask:0xf bank_mask:0xf
	v_fmac_f32_dpp v188, v82, v214 row_shr:2 row_mask:0xf bank_mask:0xf
	v_fmac_f32_dpp v189, v83, v215 row_shr:2 row_mask:0xf bank_mask:0xf
	v_fmac_f32_dpp v182, v92, v166 row_ror:1 row_mask:0xf bank_mask:0xf
	v_fmac_f32_dpp v183, v93, v167 row_ror:1 row_mask:0xf bank_mask:0xf
	v_fmac_f32_dpp v184, v94, v168 row_ror:1 row_mask:0xf bank_mask:0xf
	v_fmac_f32_dpp v185, v95, v169 row_ror:1 row_mask:0xf bank_mask:0xf
	v_fmac_f32_dpp v186, v88, v174 row_ror:1 row_mask:0xf bank_mask:0xf
	v_fmac_f32_dpp v187, v89, v175 row_ror:1 row_mask:0xf bank_mask:0xf
	v_fmac_f32_dpp v188, v90, v176 row_ror:1 row_mask:0xf bank_mask:0xf
	v_fmac_f32_dpp v189, v91, v177 row_ror:1 row_mask:0xf bank_mask:0xf
	v_fmac_f32_dpp v182, v92, v170 row_ror:2 row_mask:0xf bank_mask:0xf
	v_fmac_f32_dpp v183, v93, v171 row_ror:2 row_mask:0xf bank_mask:0xf
	v_fmac_f32_dpp v184, v94, v172 row_ror:2 row_mask:0xf bank_mask:0xf
	v_fmac_f32_dpp v185, v95, v173 row_ror:2 row_mask:0xf bank_mask:0xf
	v_fmac_f32_dpp v186, v88, v178 row_ror:2 row_mask:0xf bank_mask:0xf
	v_fmac_f32_dpp v187, v89, v179 row_ror:2 row_mask:0xf bank_mask:0xf
	v_fmac_f32_dpp v188, v90, v180 row_ror:2 row_mask:0xf bank_mask:0xf
	v_fmac_f32_dpp v189, v91, v181 row_ror:2 row_mask:0xf bank_mask:0xf
	v_pk_mul_f32 v[116:117], v[182:183], v[228:229]
	v_pk_mul_f32 v[118:119], v[184:185], v[228:229]
	v_exp_f32_e32 v116, v116
	v_exp_f32_e32 v117, v117
	v_exp_f32_e32 v118, v118
	v_exp_f32_e32 v119, v119
	v_pk_add_f32 v[116:117], v[116:117], v[230:231]
	v_pk_add_f32 v[118:119], v[118:119], v[230:231]
	v_rcp_f32_e32 v116, v116
	v_rcp_f32_e32 v117, v117
	v_rcp_f32_e32 v118, v118
	v_rcp_f32_e32 v119, v119
	v_pk_mul_f32 v[116:117], v[182:183], v[116:117]
	v_pk_mul_f32 v[118:119], v[184:185], v[118:119]
	v_pk_mul_f32 v[116:117], v[116:117], v[186:187]
	v_pk_mul_f32 v[118:119], v[118:119], v[188:189]
	v_cvt_pk_bf16_f32 v84, v116, v117
	v_cvt_pk_bf16_f32 v85, v118, v119
	v_pk_fma_f32 v[182:183], v[204:205], v[92:93], v[208:209]
	v_pk_fma_f32 v[184:185], v[206:207], v[94:95], v[210:211]
	v_pk_fma_f32 v[186:187], v[220:221], v[88:89], v[224:225]
	v_pk_fma_f32 v[188:189], v[222:223], v[90:91], v[226:227]
	v_fmac_f32_dpp v182, v92, v200 row_shr:1 row_mask:0xf bank_mask:0xf
	v_fmac_f32_dpp v183, v93, v201 row_shr:1 row_mask:0xf bank_mask:0xf
	v_fmac_f32_dpp v184, v94, v202 row_shr:1 row_mask:0xf bank_mask:0xf
	v_fmac_f32_dpp v185, v95, v203 row_shr:1 row_mask:0xf bank_mask:0xf
	v_fmac_f32_dpp v186, v88, v216 row_shr:1 row_mask:0xf bank_mask:0xf
	v_fmac_f32_dpp v187, v89, v217 row_shr:1 row_mask:0xf bank_mask:0xf
	v_fmac_f32_dpp v188, v90, v218 row_shr:1 row_mask:0xf bank_mask:0xf
	v_fmac_f32_dpp v189, v91, v219 row_shr:1 row_mask:0xf bank_mask:0xf
	v_fmac_f32_dpp v182, v92, v196 row_shr:2 row_mask:0xf bank_mask:0xf
	v_fmac_f32_dpp v183, v93, v197 row_shr:2 row_mask:0xf bank_mask:0xf
	v_fmac_f32_dpp v184, v94, v198 row_shr:2 row_mask:0xf bank_mask:0xf
	v_fmac_f32_dpp v185, v95, v199 row_shr:2 row_mask:0xf bank_mask:0xf
	v_fmac_f32_dpp v186, v88, v212 row_shr:2 row_mask:0xf bank_mask:0xf
	v_fmac_f32_dpp v187, v89, v213 row_shr:2 row_mask:0xf bank_mask:0xf
	v_fmac_f32_dpp v188, v90, v214 row_shr:2 row_mask:0xf bank_mask:0xf
	v_fmac_f32_dpp v189, v91, v215 row_shr:2 row_mask:0xf bank_mask:0xf
	global_load_dwordx4 v[196:199], v128, s[74:75] offset:16
	global_load_dwordx4 v[200:203], v128, s[76:77] offset:16
	global_load_dwordx4 v[204:207], v128, s[78:79] offset:16
	global_load_dwordx4 v[208:211], v128, s[86:87] offset:16
	global_load_dwordx4 v[212:215], v128, s[80:81] offset:16
	global_load_dwordx4 v[216:219], v128, s[82:83] offset:16
	global_load_dwordx4 v[220:223], v128, s[84:85] offset:16
	global_load_dwordx4 v[224:227], v128, s[88:89] offset:16
	v_pk_mul_f32 v[116:117], v[182:183], v[228:229]
	v_pk_mul_f32 v[118:119], v[184:185], v[228:229]
	v_exp_f32_e32 v116, v116
	v_exp_f32_e32 v117, v117
	v_exp_f32_e32 v118, v118
	v_exp_f32_e32 v119, v119
	v_pk_add_f32 v[116:117], v[116:117], v[230:231]
	v_pk_add_f32 v[118:119], v[118:119], v[230:231]
	v_rcp_f32_e32 v116, v116
	v_rcp_f32_e32 v117, v117
	v_rcp_f32_e32 v118, v118
	v_rcp_f32_e32 v119, v119
	v_pk_mul_f32 v[116:117], v[182:183], v[116:117]
	v_pk_mul_f32 v[118:119], v[184:185], v[118:119]
	v_pk_mul_f32 v[116:117], v[116:117], v[186:187]
	v_pk_mul_f32 v[118:119], v[118:119], v[188:189]
	v_cvt_pk_bf16_f32 v92, v116, v117
	v_cvt_pk_bf16_f32 v93, v118, v119
	s_waitcnt vmcnt(0)
	v_cndmask_b32_e64 v166, 0, v200, s[52:53]
	v_cndmask_b32_e64 v170, 0, v196, s[0:1]
	v_cndmask_b32_e64 v174, 0, v216, s[52:53]
	v_cndmask_b32_e64 v178, 0, v212, s[0:1]
	v_cndmask_b32_e64 v167, 0, v201, s[52:53]
	v_cndmask_b32_e64 v171, 0, v197, s[0:1]
	v_cndmask_b32_e64 v175, 0, v217, s[52:53]
	v_cndmask_b32_e64 v179, 0, v213, s[0:1]
	v_cndmask_b32_e64 v168, 0, v202, s[52:53]
	v_cndmask_b32_e64 v172, 0, v198, s[0:1]
	v_cndmask_b32_e64 v176, 0, v218, s[52:53]
	v_cndmask_b32_e64 v180, 0, v214, s[0:1]
	v_cndmask_b32_e64 v169, 0, v203, s[52:53]
	v_cndmask_b32_e64 v173, 0, v199, s[0:1]
	v_cndmask_b32_e64 v177, 0, v219, s[52:53]
	v_cndmask_b32_e64 v181, 0, v215, s[0:1]
	v_pk_fma_f32 v[182:183], v[204:205], v[36:37], v[208:209]
	v_pk_fma_f32 v[184:185], v[206:207], v[38:39], v[210:211]
	v_pk_fma_f32 v[186:187], v[220:221], v[32:33], v[224:225]
	v_pk_fma_f32 v[188:189], v[222:223], v[34:35], v[226:227]
	v_fmac_f32_dpp v182, v36, v200 row_shr:1 row_mask:0xf bank_mask:0xf
	v_fmac_f32_dpp v183, v37, v201 row_shr:1 row_mask:0xf bank_mask:0xf
	v_fmac_f32_dpp v184, v38, v202 row_shr:1 row_mask:0xf bank_mask:0xf
	v_fmac_f32_dpp v185, v39, v203 row_shr:1 row_mask:0xf bank_mask:0xf
	v_fmac_f32_dpp v186, v32, v216 row_shr:1 row_mask:0xf bank_mask:0xf
	v_fmac_f32_dpp v187, v33, v217 row_shr:1 row_mask:0xf bank_mask:0xf
	v_fmac_f32_dpp v188, v34, v218 row_shr:1 row_mask:0xf bank_mask:0xf
	v_fmac_f32_dpp v189, v35, v219 row_shr:1 row_mask:0xf bank_mask:0xf
	v_fmac_f32_dpp v182, v36, v196 row_shr:2 row_mask:0xf bank_mask:0xf
	v_fmac_f32_dpp v183, v37, v197 row_shr:2 row_mask:0xf bank_mask:0xf
	v_fmac_f32_dpp v184, v38, v198 row_shr:2 row_mask:0xf bank_mask:0xf
	v_fmac_f32_dpp v185, v39, v199 row_shr:2 row_mask:0xf bank_mask:0xf
	v_fmac_f32_dpp v186, v32, v212 row_shr:2 row_mask:0xf bank_mask:0xf
	v_fmac_f32_dpp v187, v33, v213 row_shr:2 row_mask:0xf bank_mask:0xf
	v_fmac_f32_dpp v188, v34, v214 row_shr:2 row_mask:0xf bank_mask:0xf
	v_fmac_f32_dpp v189, v35, v215 row_shr:2 row_mask:0xf bank_mask:0xf
	v_fmac_f32_dpp v182, v44, v166 row_ror:1 row_mask:0xf bank_mask:0xf
	v_fmac_f32_dpp v183, v45, v167 row_ror:1 row_mask:0xf bank_mask:0xf
	v_fmac_f32_dpp v184, v46, v168 row_ror:1 row_mask:0xf bank_mask:0xf
	v_fmac_f32_dpp v185, v47, v169 row_ror:1 row_mask:0xf bank_mask:0xf
	v_fmac_f32_dpp v186, v40, v174 row_ror:1 row_mask:0xf bank_mask:0xf
	v_fmac_f32_dpp v187, v41, v175 row_ror:1 row_mask:0xf bank_mask:0xf
	v_fmac_f32_dpp v188, v42, v176 row_ror:1 row_mask:0xf bank_mask:0xf
	v_fmac_f32_dpp v189, v43, v177 row_ror:1 row_mask:0xf bank_mask:0xf
	v_fmac_f32_dpp v182, v44, v170 row_ror:2 row_mask:0xf bank_mask:0xf
	v_fmac_f32_dpp v183, v45, v171 row_ror:2 row_mask:0xf bank_mask:0xf
	v_fmac_f32_dpp v184, v46, v172 row_ror:2 row_mask:0xf bank_mask:0xf
	v_fmac_f32_dpp v185, v47, v173 row_ror:2 row_mask:0xf bank_mask:0xf
	v_fmac_f32_dpp v186, v40, v178 row_ror:2 row_mask:0xf bank_mask:0xf
	v_fmac_f32_dpp v187, v41, v179 row_ror:2 row_mask:0xf bank_mask:0xf
	v_fmac_f32_dpp v188, v42, v180 row_ror:2 row_mask:0xf bank_mask:0xf
	v_fmac_f32_dpp v189, v43, v181 row_ror:2 row_mask:0xf bank_mask:0xf
	v_pk_mul_f32 v[116:117], v[182:183], v[228:229]
	v_pk_mul_f32 v[118:119], v[184:185], v[228:229]
	v_exp_f32_e32 v116, v116
	v_exp_f32_e32 v117, v117
	v_exp_f32_e32 v118, v118
	v_exp_f32_e32 v119, v119
	v_pk_add_f32 v[116:117], v[116:117], v[230:231]
	v_pk_add_f32 v[118:119], v[118:119], v[230:231]
	v_rcp_f32_e32 v116, v116
	v_rcp_f32_e32 v117, v117
	v_rcp_f32_e32 v118, v118
	v_rcp_f32_e32 v119, v119
	v_pk_mul_f32 v[116:117], v[182:183], v[116:117]
	v_pk_mul_f32 v[118:119], v[184:185], v[118:119]
	v_pk_mul_f32 v[116:117], v[116:117], v[186:187]
	v_pk_mul_f32 v[118:119], v[118:119], v[188:189]
	v_cvt_pk_bf16_f32 v102, v116, v117
	v_cvt_pk_bf16_f32 v103, v118, v119
	v_add_u32_e32 v132, 0x42000, v129
	global_store_dwordx4 v132, v[100:103], s[48:49] nt
	v_pk_fma_f32 v[182:183], v[204:205], v[44:45], v[208:209]
	v_pk_fma_f32 v[184:185], v[206:207], v[46:47], v[210:211]
	v_pk_fma_f32 v[186:187], v[220:221], v[40:41], v[224:225]
	v_pk_fma_f32 v[188:189], v[222:223], v[42:43], v[226:227]
	v_fmac_f32_dpp v182, v44, v200 row_shr:1 row_mask:0xf bank_mask:0xf
	v_fmac_f32_dpp v183, v45, v201 row_shr:1 row_mask:0xf bank_mask:0xf
	v_fmac_f32_dpp v184, v46, v202 row_shr:1 row_mask:0xf bank_mask:0xf
	v_fmac_f32_dpp v185, v47, v203 row_shr:1 row_mask:0xf bank_mask:0xf
	v_fmac_f32_dpp v186, v40, v216 row_shr:1 row_mask:0xf bank_mask:0xf
	v_fmac_f32_dpp v187, v41, v217 row_shr:1 row_mask:0xf bank_mask:0xf
	v_fmac_f32_dpp v188, v42, v218 row_shr:1 row_mask:0xf bank_mask:0xf
	v_fmac_f32_dpp v189, v43, v219 row_shr:1 row_mask:0xf bank_mask:0xf
	v_fmac_f32_dpp v182, v44, v196 row_shr:2 row_mask:0xf bank_mask:0xf
	v_fmac_f32_dpp v183, v45, v197 row_shr:2 row_mask:0xf bank_mask:0xf
	v_fmac_f32_dpp v184, v46, v198 row_shr:2 row_mask:0xf bank_mask:0xf
	v_fmac_f32_dpp v185, v47, v199 row_shr:2 row_mask:0xf bank_mask:0xf
	v_fmac_f32_dpp v186, v40, v212 row_shr:2 row_mask:0xf bank_mask:0xf
	v_fmac_f32_dpp v187, v41, v213 row_shr:2 row_mask:0xf bank_mask:0xf
	v_fmac_f32_dpp v188, v42, v214 row_shr:2 row_mask:0xf bank_mask:0xf
	v_fmac_f32_dpp v189, v43, v215 row_shr:2 row_mask:0xf bank_mask:0xf
	v_fmac_f32_dpp v182, v52, v166 row_ror:1 row_mask:0xf bank_mask:0xf
	v_fmac_f32_dpp v183, v53, v167 row_ror:1 row_mask:0xf bank_mask:0xf
	v_fmac_f32_dpp v184, v54, v168 row_ror:1 row_mask:0xf bank_mask:0xf
	v_fmac_f32_dpp v185, v55, v169 row_ror:1 row_mask:0xf bank_mask:0xf
	v_fmac_f32_dpp v186, v48, v174 row_ror:1 row_mask:0xf bank_mask:0xf
	v_fmac_f32_dpp v187, v49, v175 row_ror:1 row_mask:0xf bank_mask:0xf
	v_fmac_f32_dpp v188, v50, v176 row_ror:1 row_mask:0xf bank_mask:0xf
	v_fmac_f32_dpp v189, v51, v177 row_ror:1 row_mask:0xf bank_mask:0xf
	v_fmac_f32_dpp v182, v52, v170 row_ror:2 row_mask:0xf bank_mask:0xf
	v_fmac_f32_dpp v183, v53, v171 row_ror:2 row_mask:0xf bank_mask:0xf
	v_fmac_f32_dpp v184, v54, v172 row_ror:2 row_mask:0xf bank_mask:0xf
	v_fmac_f32_dpp v185, v55, v173 row_ror:2 row_mask:0xf bank_mask:0xf
	v_fmac_f32_dpp v186, v48, v178 row_ror:2 row_mask:0xf bank_mask:0xf
	v_fmac_f32_dpp v187, v49, v179 row_ror:2 row_mask:0xf bank_mask:0xf
	v_fmac_f32_dpp v188, v50, v180 row_ror:2 row_mask:0xf bank_mask:0xf
	v_fmac_f32_dpp v189, v51, v181 row_ror:2 row_mask:0xf bank_mask:0xf
	v_pk_mul_f32 v[116:117], v[182:183], v[228:229]
	v_pk_mul_f32 v[118:119], v[184:185], v[228:229]
	v_exp_f32_e32 v116, v116
	v_exp_f32_e32 v117, v117
	v_exp_f32_e32 v118, v118
	v_exp_f32_e32 v119, v119
	v_pk_add_f32 v[116:117], v[116:117], v[230:231]
	v_pk_add_f32 v[118:119], v[118:119], v[230:231]
	v_rcp_f32_e32 v116, v116
	v_rcp_f32_e32 v117, v117
	v_rcp_f32_e32 v118, v118
	v_rcp_f32_e32 v119, v119
	v_pk_mul_f32 v[116:117], v[182:183], v[116:117]
	v_pk_mul_f32 v[118:119], v[184:185], v[118:119]
	v_pk_mul_f32 v[116:117], v[116:117], v[186:187]
	v_pk_mul_f32 v[118:119], v[118:119], v[188:189]
	v_cvt_pk_bf16_f32 v114, v116, v117
	v_cvt_pk_bf16_f32 v115, v118, v119
	v_add_u32_e32 v132, 0x2c000, v129
	global_store_dwordx4 v132, v[112:115], s[48:49] nt
	v_pk_fma_f32 v[182:183], v[204:205], v[52:53], v[208:209]
	v_pk_fma_f32 v[184:185], v[206:207], v[54:55], v[210:211]
	v_pk_fma_f32 v[186:187], v[220:221], v[48:49], v[224:225]
	v_pk_fma_f32 v[188:189], v[222:223], v[50:51], v[226:227]
	v_fmac_f32_dpp v182, v52, v200 row_shr:1 row_mask:0xf bank_mask:0xf
	v_fmac_f32_dpp v183, v53, v201 row_shr:1 row_mask:0xf bank_mask:0xf
	v_fmac_f32_dpp v184, v54, v202 row_shr:1 row_mask:0xf bank_mask:0xf
	v_fmac_f32_dpp v185, v55, v203 row_shr:1 row_mask:0xf bank_mask:0xf
	v_fmac_f32_dpp v186, v48, v216 row_shr:1 row_mask:0xf bank_mask:0xf
	v_fmac_f32_dpp v187, v49, v217 row_shr:1 row_mask:0xf bank_mask:0xf
	v_fmac_f32_dpp v188, v50, v218 row_shr:1 row_mask:0xf bank_mask:0xf
	v_fmac_f32_dpp v189, v51, v219 row_shr:1 row_mask:0xf bank_mask:0xf
	v_fmac_f32_dpp v182, v52, v196 row_shr:2 row_mask:0xf bank_mask:0xf
	v_fmac_f32_dpp v183, v53, v197 row_shr:2 row_mask:0xf bank_mask:0xf
	v_fmac_f32_dpp v184, v54, v198 row_shr:2 row_mask:0xf bank_mask:0xf
	v_fmac_f32_dpp v185, v55, v199 row_shr:2 row_mask:0xf bank_mask:0xf
	v_fmac_f32_dpp v186, v48, v212 row_shr:2 row_mask:0xf bank_mask:0xf
	v_fmac_f32_dpp v187, v49, v213 row_shr:2 row_mask:0xf bank_mask:0xf
	v_fmac_f32_dpp v188, v50, v214 row_shr:2 row_mask:0xf bank_mask:0xf
	v_fmac_f32_dpp v189, v51, v215 row_shr:2 row_mask:0xf bank_mask:0xf
	v_fmac_f32_dpp v182, v60, v166 row_ror:1 row_mask:0xf bank_mask:0xf
	v_fmac_f32_dpp v183, v61, v167 row_ror:1 row_mask:0xf bank_mask:0xf
	v_fmac_f32_dpp v184, v62, v168 row_ror:1 row_mask:0xf bank_mask:0xf
	v_fmac_f32_dpp v185, v63, v169 row_ror:1 row_mask:0xf bank_mask:0xf
	v_fmac_f32_dpp v186, v56, v174 row_ror:1 row_mask:0xf bank_mask:0xf
	v_fmac_f32_dpp v187, v57, v175 row_ror:1 row_mask:0xf bank_mask:0xf
	v_fmac_f32_dpp v188, v58, v176 row_ror:1 row_mask:0xf bank_mask:0xf
	v_fmac_f32_dpp v189, v59, v177 row_ror:1 row_mask:0xf bank_mask:0xf
	v_fmac_f32_dpp v182, v60, v170 row_ror:2 row_mask:0xf bank_mask:0xf
	v_fmac_f32_dpp v183, v61, v171 row_ror:2 row_mask:0xf bank_mask:0xf
	v_fmac_f32_dpp v184, v62, v172 row_ror:2 row_mask:0xf bank_mask:0xf
	v_fmac_f32_dpp v185, v63, v173 row_ror:2 row_mask:0xf bank_mask:0xf
	v_fmac_f32_dpp v186, v56, v178 row_ror:2 row_mask:0xf bank_mask:0xf
	v_fmac_f32_dpp v187, v57, v179 row_ror:2 row_mask:0xf bank_mask:0xf
	v_fmac_f32_dpp v188, v58, v180 row_ror:2 row_mask:0xf bank_mask:0xf
	v_fmac_f32_dpp v189, v59, v181 row_ror:2 row_mask:0xf bank_mask:0xf
	v_pk_mul_f32 v[116:117], v[182:183], v[228:229]
	v_pk_mul_f32 v[118:119], v[184:185], v[228:229]
	v_exp_f32_e32 v116, v116
	v_exp_f32_e32 v117, v117
	v_exp_f32_e32 v118, v118
	v_exp_f32_e32 v119, v119
	v_pk_add_f32 v[116:117], v[116:117], v[230:231]
	v_pk_add_f32 v[118:119], v[118:119], v[230:231]
	v_rcp_f32_e32 v116, v116
	v_rcp_f32_e32 v117, v117
	v_rcp_f32_e32 v118, v118
	v_rcp_f32_e32 v119, v119
	v_pk_mul_f32 v[116:117], v[182:183], v[116:117]
	v_pk_mul_f32 v[118:119], v[184:185], v[118:119]
	v_pk_mul_f32 v[116:117], v[116:117], v[186:187]
	v_pk_mul_f32 v[118:119], v[118:119], v[188:189]
	v_cvt_pk_bf16_f32 v140, v116, v117
	v_cvt_pk_bf16_f32 v141, v118, v119
	v_add_u32_e32 v132, 0x16000, v129
	global_store_dwordx4 v132, v[138:141], s[48:49] nt
	v_pk_fma_f32 v[182:183], v[204:205], v[60:61], v[208:209]
	v_pk_fma_f32 v[184:185], v[206:207], v[62:63], v[210:211]
	v_pk_fma_f32 v[186:187], v[220:221], v[56:57], v[224:225]
	v_pk_fma_f32 v[188:189], v[222:223], v[58:59], v[226:227]
	v_fmac_f32_dpp v182, v60, v200 row_shr:1 row_mask:0xf bank_mask:0xf
	v_fmac_f32_dpp v183, v61, v201 row_shr:1 row_mask:0xf bank_mask:0xf
	v_fmac_f32_dpp v184, v62, v202 row_shr:1 row_mask:0xf bank_mask:0xf
	v_fmac_f32_dpp v185, v63, v203 row_shr:1 row_mask:0xf bank_mask:0xf
	v_fmac_f32_dpp v186, v56, v216 row_shr:1 row_mask:0xf bank_mask:0xf
	v_fmac_f32_dpp v187, v57, v217 row_shr:1 row_mask:0xf bank_mask:0xf
	v_fmac_f32_dpp v188, v58, v218 row_shr:1 row_mask:0xf bank_mask:0xf
	v_fmac_f32_dpp v189, v59, v219 row_shr:1 row_mask:0xf bank_mask:0xf
	v_fmac_f32_dpp v182, v60, v196 row_shr:2 row_mask:0xf bank_mask:0xf
	v_fmac_f32_dpp v183, v61, v197 row_shr:2 row_mask:0xf bank_mask:0xf
	v_fmac_f32_dpp v184, v62, v198 row_shr:2 row_mask:0xf bank_mask:0xf
	v_fmac_f32_dpp v185, v63, v199 row_shr:2 row_mask:0xf bank_mask:0xf
	v_fmac_f32_dpp v186, v56, v212 row_shr:2 row_mask:0xf bank_mask:0xf
	v_fmac_f32_dpp v187, v57, v213 row_shr:2 row_mask:0xf bank_mask:0xf
	v_fmac_f32_dpp v188, v58, v214 row_shr:2 row_mask:0xf bank_mask:0xf
	v_fmac_f32_dpp v189, v59, v215 row_shr:2 row_mask:0xf bank_mask:0xf
	v_pk_mul_f32 v[116:117], v[182:183], v[228:229]
	v_pk_mul_f32 v[118:119], v[184:185], v[228:229]
	v_exp_f32_e32 v116, v116
	v_exp_f32_e32 v117, v117
	v_exp_f32_e32 v118, v118
	v_exp_f32_e32 v119, v119
	v_pk_add_f32 v[116:117], v[116:117], v[230:231]
	v_pk_add_f32 v[118:119], v[118:119], v[230:231]
	v_rcp_f32_e32 v116, v116
	v_rcp_f32_e32 v117, v117
	v_rcp_f32_e32 v118, v118
	v_rcp_f32_e32 v119, v119
	v_pk_mul_f32 v[116:117], v[182:183], v[116:117]
	v_pk_mul_f32 v[118:119], v[184:185], v[118:119]
	v_pk_mul_f32 v[116:117], v[116:117], v[186:187]
	v_pk_mul_f32 v[118:119], v[118:119], v[188:189]
	v_cvt_pk_bf16_f32 v144, v116, v117
	v_cvt_pk_bf16_f32 v145, v118, v119
	s_mov_b64 exec, s[4:5]
	global_store_dwordx4 v129, v[142:145], s[48:49] nt
	s_mov_b64 exec, -1
	v_pk_fma_f32 v[182:183], v[204:205], v[4:5], v[208:209]
	v_pk_fma_f32 v[184:185], v[206:207], v[6:7], v[210:211]
	v_pk_fma_f32 v[186:187], v[220:221], v[0:1], v[224:225]
	v_pk_fma_f32 v[188:189], v[222:223], v[2:3], v[226:227]
	v_fmac_f32_dpp v182, v4, v200 row_shr:1 row_mask:0xf bank_mask:0xf
	v_fmac_f32_dpp v183, v5, v201 row_shr:1 row_mask:0xf bank_mask:0xf
	v_fmac_f32_dpp v184, v6, v202 row_shr:1 row_mask:0xf bank_mask:0xf
	v_fmac_f32_dpp v185, v7, v203 row_shr:1 row_mask:0xf bank_mask:0xf
	v_fmac_f32_dpp v186, v0, v216 row_shr:1 row_mask:0xf bank_mask:0xf
	v_fmac_f32_dpp v187, v1, v217 row_shr:1 row_mask:0xf bank_mask:0xf
	v_fmac_f32_dpp v188, v2, v218 row_shr:1 row_mask:0xf bank_mask:0xf
	v_fmac_f32_dpp v189, v3, v219 row_shr:1 row_mask:0xf bank_mask:0xf
	v_fmac_f32_dpp v182, v4, v196 row_shr:2 row_mask:0xf bank_mask:0xf
	v_fmac_f32_dpp v183, v5, v197 row_shr:2 row_mask:0xf bank_mask:0xf
	v_fmac_f32_dpp v184, v6, v198 row_shr:2 row_mask:0xf bank_mask:0xf
	v_fmac_f32_dpp v185, v7, v199 row_shr:2 row_mask:0xf bank_mask:0xf
	v_fmac_f32_dpp v186, v0, v212 row_shr:2 row_mask:0xf bank_mask:0xf
	v_fmac_f32_dpp v187, v1, v213 row_shr:2 row_mask:0xf bank_mask:0xf
	v_fmac_f32_dpp v188, v2, v214 row_shr:2 row_mask:0xf bank_mask:0xf
	v_fmac_f32_dpp v189, v3, v215 row_shr:2 row_mask:0xf bank_mask:0xf
	v_fmac_f32_dpp v182, v12, v166 row_ror:1 row_mask:0xf bank_mask:0xf
	v_fmac_f32_dpp v183, v13, v167 row_ror:1 row_mask:0xf bank_mask:0xf
	v_fmac_f32_dpp v184, v14, v168 row_ror:1 row_mask:0xf bank_mask:0xf
	v_fmac_f32_dpp v185, v15, v169 row_ror:1 row_mask:0xf bank_mask:0xf
	v_fmac_f32_dpp v186, v8, v174 row_ror:1 row_mask:0xf bank_mask:0xf
	v_fmac_f32_dpp v187, v9, v175 row_ror:1 row_mask:0xf bank_mask:0xf
	v_fmac_f32_dpp v188, v10, v176 row_ror:1 row_mask:0xf bank_mask:0xf
	v_fmac_f32_dpp v189, v11, v177 row_ror:1 row_mask:0xf bank_mask:0xf
	v_fmac_f32_dpp v182, v12, v170 row_ror:2 row_mask:0xf bank_mask:0xf
	v_fmac_f32_dpp v183, v13, v171 row_ror:2 row_mask:0xf bank_mask:0xf
	v_fmac_f32_dpp v184, v14, v172 row_ror:2 row_mask:0xf bank_mask:0xf
	v_fmac_f32_dpp v185, v15, v173 row_ror:2 row_mask:0xf bank_mask:0xf
	v_fmac_f32_dpp v186, v8, v178 row_ror:2 row_mask:0xf bank_mask:0xf
	v_fmac_f32_dpp v187, v9, v179 row_ror:2 row_mask:0xf bank_mask:0xf
	v_fmac_f32_dpp v188, v10, v180 row_ror:2 row_mask:0xf bank_mask:0xf
	v_fmac_f32_dpp v189, v11, v181 row_ror:2 row_mask:0xf bank_mask:0xf
	v_pk_mul_f32 v[116:117], v[182:183], v[228:229]
	v_pk_mul_f32 v[118:119], v[184:185], v[228:229]
	v_exp_f32_e32 v116, v116
	v_exp_f32_e32 v117, v117
	v_exp_f32_e32 v118, v118
	v_exp_f32_e32 v119, v119
	v_pk_add_f32 v[116:117], v[116:117], v[230:231]
	v_pk_add_f32 v[118:119], v[118:119], v[230:231]
	v_rcp_f32_e32 v116, v116
	v_rcp_f32_e32 v117, v117
	v_rcp_f32_e32 v118, v118
	v_rcp_f32_e32 v119, v119
	v_pk_mul_f32 v[116:117], v[182:183], v[116:117]
	v_pk_mul_f32 v[118:119], v[184:185], v[118:119]
	v_pk_mul_f32 v[116:117], v[116:117], v[186:187]
	v_pk_mul_f32 v[118:119], v[118:119], v[188:189]
	v_cvt_pk_bf16_f32 v70, v116, v117
	v_cvt_pk_bf16_f32 v71, v118, v119
	v_add_u32_e32 v132, 0xf2000, v129
	global_store_dwordx4 v132, v[68:71], s[48:49] nt
	v_pk_fma_f32 v[182:183], v[204:205], v[12:13], v[208:209]
	v_pk_fma_f32 v[184:185], v[206:207], v[14:15], v[210:211]
	v_pk_fma_f32 v[186:187], v[220:221], v[8:9], v[224:225]
	v_pk_fma_f32 v[188:189], v[222:223], v[10:11], v[226:227]
	v_fmac_f32_dpp v182, v12, v200 row_shr:1 row_mask:0xf bank_mask:0xf
	v_fmac_f32_dpp v183, v13, v201 row_shr:1 row_mask:0xf bank_mask:0xf
	v_fmac_f32_dpp v184, v14, v202 row_shr:1 row_mask:0xf bank_mask:0xf
	v_fmac_f32_dpp v185, v15, v203 row_shr:1 row_mask:0xf bank_mask:0xf
	v_fmac_f32_dpp v186, v8, v216 row_shr:1 row_mask:0xf bank_mask:0xf
	v_fmac_f32_dpp v187, v9, v217 row_shr:1 row_mask:0xf bank_mask:0xf
	v_fmac_f32_dpp v188, v10, v218 row_shr:1 row_mask:0xf bank_mask:0xf
	v_fmac_f32_dpp v189, v11, v219 row_shr:1 row_mask:0xf bank_mask:0xf
	v_fmac_f32_dpp v182, v12, v196 row_shr:2 row_mask:0xf bank_mask:0xf
	v_fmac_f32_dpp v183, v13, v197 row_shr:2 row_mask:0xf bank_mask:0xf
	v_fmac_f32_dpp v184, v14, v198 row_shr:2 row_mask:0xf bank_mask:0xf
	v_fmac_f32_dpp v185, v15, v199 row_shr:2 row_mask:0xf bank_mask:0xf
	v_fmac_f32_dpp v186, v8, v212 row_shr:2 row_mask:0xf bank_mask:0xf
	v_fmac_f32_dpp v187, v9, v213 row_shr:2 row_mask:0xf bank_mask:0xf
	v_fmac_f32_dpp v188, v10, v214 row_shr:2 row_mask:0xf bank_mask:0xf
	v_fmac_f32_dpp v189, v11, v215 row_shr:2 row_mask:0xf bank_mask:0xf
	v_fmac_f32_dpp v182, v20, v166 row_ror:1 row_mask:0xf bank_mask:0xf
	v_fmac_f32_dpp v183, v21, v167 row_ror:1 row_mask:0xf bank_mask:0xf
	v_fmac_f32_dpp v184, v22, v168 row_ror:1 row_mask:0xf bank_mask:0xf
	v_fmac_f32_dpp v185, v23, v169 row_ror:1 row_mask:0xf bank_mask:0xf
	v_fmac_f32_dpp v186, v16, v174 row_ror:1 row_mask:0xf bank_mask:0xf
	v_fmac_f32_dpp v187, v17, v175 row_ror:1 row_mask:0xf bank_mask:0xf
	v_fmac_f32_dpp v188, v18, v176 row_ror:1 row_mask:0xf bank_mask:0xf
	v_fmac_f32_dpp v189, v19, v177 row_ror:1 row_mask:0xf bank_mask:0xf
	v_fmac_f32_dpp v182, v20, v170 row_ror:2 row_mask:0xf bank_mask:0xf
	v_fmac_f32_dpp v183, v21, v171 row_ror:2 row_mask:0xf bank_mask:0xf
	v_fmac_f32_dpp v184, v22, v172 row_ror:2 row_mask:0xf bank_mask:0xf
	v_fmac_f32_dpp v185, v23, v173 row_ror:2 row_mask:0xf bank_mask:0xf
	v_fmac_f32_dpp v186, v16, v178 row_ror:2 row_mask:0xf bank_mask:0xf
	v_fmac_f32_dpp v187, v17, v179 row_ror:2 row_mask:0xf bank_mask:0xf
	v_fmac_f32_dpp v188, v18, v180 row_ror:2 row_mask:0xf bank_mask:0xf
	v_fmac_f32_dpp v189, v19, v181 row_ror:2 row_mask:0xf bank_mask:0xf
	v_pk_mul_f32 v[116:117], v[182:183], v[228:229]
	v_pk_mul_f32 v[118:119], v[184:185], v[228:229]
	v_exp_f32_e32 v116, v116
	v_exp_f32_e32 v117, v117
	v_exp_f32_e32 v118, v118
	v_exp_f32_e32 v119, v119
	v_pk_add_f32 v[116:117], v[116:117], v[230:231]
	v_pk_add_f32 v[118:119], v[118:119], v[230:231]
	v_rcp_f32_e32 v116, v116
	v_rcp_f32_e32 v117, v117
	v_rcp_f32_e32 v118, v118
	v_rcp_f32_e32 v119, v119
	v_pk_mul_f32 v[116:117], v[182:183], v[116:117]
	v_pk_mul_f32 v[118:119], v[184:185], v[118:119]
	v_pk_mul_f32 v[116:117], v[116:117], v[186:187]
	v_pk_mul_f32 v[118:119], v[118:119], v[188:189]
	v_cvt_pk_bf16_f32 v78, v116, v117
	v_cvt_pk_bf16_f32 v79, v118, v119
	v_add_u32_e32 v132, 0xdc000, v129
	global_store_dwordx4 v132, v[76:79], s[48:49] nt
	v_pk_fma_f32 v[182:183], v[204:205], v[20:21], v[208:209]
	v_pk_fma_f32 v[184:185], v[206:207], v[22:23], v[210:211]
	v_pk_fma_f32 v[186:187], v[220:221], v[16:17], v[224:225]
	v_pk_fma_f32 v[188:189], v[222:223], v[18:19], v[226:227]
	v_fmac_f32_dpp v182, v20, v200 row_shr:1 row_mask:0xf bank_mask:0xf
	v_fmac_f32_dpp v183, v21, v201 row_shr:1 row_mask:0xf bank_mask:0xf
	v_fmac_f32_dpp v184, v22, v202 row_shr:1 row_mask:0xf bank_mask:0xf
	v_fmac_f32_dpp v185, v23, v203 row_shr:1 row_mask:0xf bank_mask:0xf
	v_fmac_f32_dpp v186, v16, v216 row_shr:1 row_mask:0xf bank_mask:0xf
	v_fmac_f32_dpp v187, v17, v217 row_shr:1 row_mask:0xf bank_mask:0xf
	v_fmac_f32_dpp v188, v18, v218 row_shr:1 row_mask:0xf bank_mask:0xf
	v_fmac_f32_dpp v189, v19, v219 row_shr:1 row_mask:0xf bank_mask:0xf
	v_fmac_f32_dpp v182, v20, v196 row_shr:2 row_mask:0xf bank_mask:0xf
	v_fmac_f32_dpp v183, v21, v197 row_shr:2 row_mask:0xf bank_mask:0xf
	v_fmac_f32_dpp v184, v22, v198 row_shr:2 row_mask:0xf bank_mask:0xf
	v_fmac_f32_dpp v185, v23, v199 row_shr:2 row_mask:0xf bank_mask:0xf
	v_fmac_f32_dpp v186, v16, v212 row_shr:2 row_mask:0xf bank_mask:0xf
	v_fmac_f32_dpp v187, v17, v213 row_shr:2 row_mask:0xf bank_mask:0xf
	v_fmac_f32_dpp v188, v18, v214 row_shr:2 row_mask:0xf bank_mask:0xf
	v_fmac_f32_dpp v189, v19, v215 row_shr:2 row_mask:0xf bank_mask:0xf
	v_fmac_f32_dpp v182, v28, v166 row_ror:1 row_mask:0xf bank_mask:0xf
	v_fmac_f32_dpp v183, v29, v167 row_ror:1 row_mask:0xf bank_mask:0xf
	v_fmac_f32_dpp v184, v30, v168 row_ror:1 row_mask:0xf bank_mask:0xf
	v_fmac_f32_dpp v185, v31, v169 row_ror:1 row_mask:0xf bank_mask:0xf
	v_fmac_f32_dpp v186, v24, v174 row_ror:1 row_mask:0xf bank_mask:0xf
	v_fmac_f32_dpp v187, v25, v175 row_ror:1 row_mask:0xf bank_mask:0xf
	v_fmac_f32_dpp v188, v26, v176 row_ror:1 row_mask:0xf bank_mask:0xf
	v_fmac_f32_dpp v189, v27, v177 row_ror:1 row_mask:0xf bank_mask:0xf
	v_fmac_f32_dpp v182, v28, v170 row_ror:2 row_mask:0xf bank_mask:0xf
	v_fmac_f32_dpp v183, v29, v171 row_ror:2 row_mask:0xf bank_mask:0xf
	v_fmac_f32_dpp v184, v30, v172 row_ror:2 row_mask:0xf bank_mask:0xf
	v_fmac_f32_dpp v185, v31, v173 row_ror:2 row_mask:0xf bank_mask:0xf
	v_fmac_f32_dpp v186, v24, v178 row_ror:2 row_mask:0xf bank_mask:0xf
	v_fmac_f32_dpp v187, v25, v179 row_ror:2 row_mask:0xf bank_mask:0xf
	v_fmac_f32_dpp v188, v26, v180 row_ror:2 row_mask:0xf bank_mask:0xf
	v_fmac_f32_dpp v189, v27, v181 row_ror:2 row_mask:0xf bank_mask:0xf
	v_pk_mul_f32 v[116:117], v[182:183], v[228:229]
	v_pk_mul_f32 v[118:119], v[184:185], v[228:229]
	v_exp_f32_e32 v116, v116
	v_exp_f32_e32 v117, v117
	v_exp_f32_e32 v118, v118
	v_exp_f32_e32 v119, v119
	v_pk_add_f32 v[116:117], v[116:117], v[230:231]
	v_pk_add_f32 v[118:119], v[118:119], v[230:231]
	v_rcp_f32_e32 v116, v116
	v_rcp_f32_e32 v117, v117
	v_rcp_f32_e32 v118, v118
	v_rcp_f32_e32 v119, v119
	v_pk_mul_f32 v[116:117], v[182:183], v[116:117]
	v_pk_mul_f32 v[118:119], v[184:185], v[118:119]
	v_pk_mul_f32 v[116:117], v[116:117], v[186:187]
	v_pk_mul_f32 v[118:119], v[118:119], v[188:189]
	v_cvt_pk_bf16_f32 v86, v116, v117
	v_cvt_pk_bf16_f32 v87, v118, v119
	v_add_u32_e32 v132, 0xc6000, v129
	global_store_dwordx4 v132, v[84:87], s[48:49] nt
	v_pk_fma_f32 v[182:183], v[204:205], v[28:29], v[208:209]
	v_pk_fma_f32 v[184:185], v[206:207], v[30:31], v[210:211]
	v_pk_fma_f32 v[186:187], v[220:221], v[24:25], v[224:225]
	v_pk_fma_f32 v[188:189], v[222:223], v[26:27], v[226:227]
	v_fmac_f32_dpp v182, v28, v200 row_shr:1 row_mask:0xf bank_mask:0xf
	v_fmac_f32_dpp v183, v29, v201 row_shr:1 row_mask:0xf bank_mask:0xf
	v_fmac_f32_dpp v184, v30, v202 row_shr:1 row_mask:0xf bank_mask:0xf
	v_fmac_f32_dpp v185, v31, v203 row_shr:1 row_mask:0xf bank_mask:0xf
	v_fmac_f32_dpp v186, v24, v216 row_shr:1 row_mask:0xf bank_mask:0xf
	v_fmac_f32_dpp v187, v25, v217 row_shr:1 row_mask:0xf bank_mask:0xf
	v_fmac_f32_dpp v188, v26, v218 row_shr:1 row_mask:0xf bank_mask:0xf
	v_fmac_f32_dpp v189, v27, v219 row_shr:1 row_mask:0xf bank_mask:0xf
	v_fmac_f32_dpp v182, v28, v196 row_shr:2 row_mask:0xf bank_mask:0xf
	v_fmac_f32_dpp v183, v29, v197 row_shr:2 row_mask:0xf bank_mask:0xf
	v_fmac_f32_dpp v184, v30, v198 row_shr:2 row_mask:0xf bank_mask:0xf
	v_fmac_f32_dpp v185, v31, v199 row_shr:2 row_mask:0xf bank_mask:0xf
	v_fmac_f32_dpp v186, v24, v212 row_shr:2 row_mask:0xf bank_mask:0xf
	v_fmac_f32_dpp v187, v25, v213 row_shr:2 row_mask:0xf bank_mask:0xf
	v_fmac_f32_dpp v188, v26, v214 row_shr:2 row_mask:0xf bank_mask:0xf
	v_fmac_f32_dpp v189, v27, v215 row_shr:2 row_mask:0xf bank_mask:0xf
	v_pk_mul_f32 v[116:117], v[182:183], v[228:229]
	v_pk_mul_f32 v[118:119], v[184:185], v[228:229]
	v_exp_f32_e32 v116, v116
	v_exp_f32_e32 v117, v117
	v_exp_f32_e32 v118, v118
	v_exp_f32_e32 v119, v119
	v_pk_add_f32 v[116:117], v[116:117], v[230:231]
	v_pk_add_f32 v[118:119], v[118:119], v[230:231]
	v_rcp_f32_e32 v116, v116
	v_rcp_f32_e32 v117, v117
	v_rcp_f32_e32 v118, v118
	v_rcp_f32_e32 v119, v119
	v_pk_mul_f32 v[116:117], v[182:183], v[116:117]
	v_pk_mul_f32 v[118:119], v[184:185], v[118:119]
	v_pk_mul_f32 v[116:117], v[116:117], v[186:187]
	v_pk_mul_f32 v[118:119], v[118:119], v[188:189]
	v_cvt_pk_bf16_f32 v94, v116, v117
	v_cvt_pk_bf16_f32 v95, v118, v119
	v_add_u32_e32 v132, 0xb0000, v129
	s_mov_b64 exec, s[4:5]
	global_store_dwordx4 v132, v[92:95], s[48:49] nt
	s_mov_b64 exec, -1
